# grid barrier: last-arriving leader of each XCD no longer issues (and waits for) the per-XCD generation atomic that nothing reads since leaders poll the top-level generation
# speedup vs baseline: 1.0016x; 1.0016x over previous
; __device__ __forceinline__ unsigned xb_ld(unsigned* p)              { return __hip_atomic_load(p, __ATOMIC_RELAXED, __HIP_MEMORY_SCOPE_AGENT); }
; __device__ __forceinline__ unsigned xb_add(unsigned* p, unsigned v) { return __hip_atomic_fetch_add(p, v, __ATOMIC_RELAXED, __HIP_MEMORY_SCOPE_AGENT); }
; #define XB_SPIN(cond, bar) do { unsigned _sp = 0; while (cond) { __builtin_amdgcn_s_sleep(1); \
;     if ((++_sp & 255u) == 0u) { if (xb_ld(&(bar)[XB_TMO])) break; if (_sp > XB_SPIN_CAP) { atomicAdd(&(bar)[XB_TMO], 1u); break; } } } } while (0)
; __device__ __forceinline__ void xcd_barrier(const XcdBarrier& b, bool leader) {
;     ...
;         if (old + 1u == (gen + 1u) * nloc) {
;             __builtin_amdgcn_fence(__ATOMIC_RELEASE, "agent");
;             asm volatile("s_waitcnt vmcnt(0)" ::: "memory");
;             const unsigned og = xb_add(&bar[XB_TOP], 1u);
;             const unsigned tg = og / nx;
;             if (og + 1u == (tg + 1u) * nx) xb_add(&bar[XB_TOPGEN], 1u);
;             else XB_SPIN(xb_ld(&bar[XB_TOPGEN]) == tg, bar);
;             __builtin_amdgcn_fence(__ATOMIC_ACQUIRE, "agent");
;             xb_add(&bar[XB_XGEN(b.x)], 1u);
;             asm volatile("s_waitcnt vmcnt(0)" ::: "memory");
.LBB0_122:
	s_or_b64 exec, exec, s[2:3]
	v_mov_b32_e32 v0, s25
	v_add_co_u32_e32 v0, vcc, 0x2000, v0
	v_mov_b32_e32 v1, s24
	s_nop 0
	v_addc_co_u32_e32 v1, vcc, 0, v1, vcc
	v_mov_b32_e32 v2, 1
	s_waitcnt vmcnt(0) lgkmcnt(0)
	buffer_inv sc1
	s_waitcnt vmcnt(0)

; __device__ __forceinline__ unsigned xb_ld(unsigned* p)              { return __hip_atomic_load(p, __ATOMIC_RELAXED, __HIP_MEMORY_SCOPE_AGENT); }
; __device__ __forceinline__ unsigned xb_add(unsigned* p, unsigned v) { return __hip_atomic_fetch_add(p, v, __ATOMIC_RELAXED, __HIP_MEMORY_SCOPE_AGENT); }
; #define XB_SPIN(cond, bar) do { unsigned _sp = 0; while (cond) { __builtin_amdgcn_s_sleep(1); \
;     if ((++_sp & 255u) == 0u) { if (xb_ld(&(bar)[XB_TMO])) break; if (_sp > XB_SPIN_CAP) { atomicAdd(&(bar)[XB_TMO], 1u); break; } } } } while (0)
; __device__ __forceinline__ void xcd_barrier(const XcdBarrier& b, bool leader) {
;     ...
;         if (old + 1u == (gen + 1u) * nloc) {
;             __builtin_amdgcn_fence(__ATOMIC_RELEASE, "agent");
;             asm volatile("s_waitcnt vmcnt(0)" ::: "memory");
;             const unsigned og = xb_add(&bar[XB_TOP], 1u);
;             const unsigned tg = og / nx;
;             if (og + 1u == (tg + 1u) * nx) xb_add(&bar[XB_TOPGEN], 1u);
;             else XB_SPIN(xb_ld(&bar[XB_TOPGEN]) == tg, bar);
;             __builtin_amdgcn_fence(__ATOMIC_ACQUIRE, "agent");
;             xb_add(&bar[XB_XGEN(b.x)], 1u);
;             asm volatile("s_waitcnt vmcnt(0)" ::: "memory");
.LBB0_1183:
	s_or_b64 exec, exec, s[4:5]
	v_mov_b32_e32 v0, s27
	v_add_co_u32_e32 v0, vcc, 0x2000, v0
	v_mov_b32_e32 v1, s26
	s_nop 0
	v_addc_co_u32_e32 v1, vcc, 0, v1, vcc
	v_mov_b32_e32 v2, 1
	s_waitcnt vmcnt(0) lgkmcnt(0)
	buffer_inv sc1
	s_waitcnt vmcnt(0)
